# k=10 tail: s_sleep pacing in the four off-critical-path weight-conversion loops that share HBM with the second-round GEMM tiles
# speedup vs baseline: 1.0053x; 1.0031x over previous
; template <int MODE> __device__ __forceinline__ void transpose_item(const float* W, int K, int N, bf16_t* WT, LAS float* scr, int item, int lane) {
;     const int nblk = N / 32, kb = item / nblk, nb = item % nblk, k0 = 64 * kb, n0 = 32 * nb;
; #pragma unroll 8
;     for (int i = 0; i < 32; ++i) { const int kk = 2 * i + (lane >> 5); scr[kk * 33 + (lane & 31)] = W[(size_t)(k0 + kk) * N + n0 + (lane & 31)]; }
.LBB0_824:
	s_lshl_b32 s10, s5, 1
	s_lshl_b32 s7, s4, 1
	v_or_b32_e32 v20, s10, v0
	v_or_b32_e32 v18, s7, v7
	v_ashrrev_i32_e32 v21, 31, v20
	v_ashrrev_i32_e32 v19, 31, v18
	v_lshlrev_b64 v[20:21], 12, v[20:21]
	v_lshlrev_b64 v[18:19], 12, v[18:19]
	v_lshl_add_u64 v[20:21], v[10:11], 0, v[20:21]
	v_lshl_add_u64 v[18:19], v[10:11], 0, v[18:19]
	global_load_dword v23, v[20:21], off
	global_load_dword v24, v[18:19], off
	v_or_b32_e32 v17, s7, v3
	v_or_b32_e32 v22, s10, v2
	v_mad_u64_u32 v[18:19], s[16:17], v22, s83, v[6:7]
	v_mad_u64_u32 v[20:21], s[16:17], v17, s83, v[6:7]
	s_add_i32 s14, s10, 4
	s_add_i32 s11, s7, 4
	v_or_b32_e32 v17, s11, v3
	v_or_b32_e32 v22, s14, v2
	s_add_i32 s5, s5, 16
	s_add_i32 s4, s4, 16
	s_add_i32 s6, s6, -16
	s_waitcnt vmcnt(1)
	ds_write_b32 v18, v23
	s_waitcnt vmcnt(0)
	ds_write_b32 v20, v24
	s_sleep 32
	v_or_b32_e32 v20, s14, v0
	v_or_b32_e32 v18, s11, v7
	v_ashrrev_i32_e32 v21, 31, v20
	v_ashrrev_i32_e32 v19, 31, v18
	v_lshlrev_b64 v[20:21], 12, v[20:21]
	v_lshlrev_b64 v[18:19], 12, v[18:19]
	v_lshl_add_u64 v[20:21], v[10:11], 0, v[20:21]
	v_lshl_add_u64 v[18:19], v[10:11], 0, v[18:19]
	global_load_dword v23, v[20:21], off
	global_load_dword v24, v[18:19], off
	v_mad_u64_u32 v[18:19], s[16:17], v22, s83, v[6:7]
	v_mad_u64_u32 v[20:21], s[16:17], v17, s83, v[6:7]
	s_add_i32 s14, s10, 8
	s_add_i32 s11, s7, 8
	v_or_b32_e32 v17, s11, v3
	v_or_b32_e32 v22, s14, v2
	s_waitcnt vmcnt(1)
	ds_write_b32 v18, v23
	s_waitcnt vmcnt(0)
	ds_write_b32 v20, v24
	s_sleep 32
	v_or_b32_e32 v20, s14, v0
	v_or_b32_e32 v18, s11, v7
	v_ashrrev_i32_e32 v21, 31, v20
	v_ashrrev_i32_e32 v19, 31, v18
	v_lshlrev_b64 v[20:21], 12, v[20:21]
	v_lshlrev_b64 v[18:19], 12, v[18:19]
	v_lshl_add_u64 v[20:21], v[10:11], 0, v[20:21]
	v_lshl_add_u64 v[18:19], v[10:11], 0, v[18:19]
	global_load_dword v23, v[20:21], off
	global_load_dword v24, v[18:19], off
	v_mad_u64_u32 v[18:19], s[16:17], v22, s83, v[6:7]
	v_mad_u64_u32 v[20:21], s[16:17], v17, s83, v[6:7]
	s_add_i32 s14, s10, 12
	s_add_i32 s11, s7, 12
	v_or_b32_e32 v17, s11, v3
	v_or_b32_e32 v22, s14, v2
	s_waitcnt vmcnt(1)
	ds_write_b32 v18, v23
	s_waitcnt vmcnt(0)
	ds_write_b32 v20, v24
	s_sleep 32
	v_or_b32_e32 v20, s14, v0
	v_or_b32_e32 v18, s11, v7
	v_ashrrev_i32_e32 v21, 31, v20
	v_ashrrev_i32_e32 v19, 31, v18
	v_lshlrev_b64 v[20:21], 12, v[20:21]
	v_lshlrev_b64 v[18:19], 12, v[18:19]
	v_lshl_add_u64 v[20:21], v[10:11], 0, v[20:21]
	v_lshl_add_u64 v[18:19], v[10:11], 0, v[18:19]
	global_load_dword v23, v[20:21], off
	global_load_dword v24, v[18:19], off
	v_mad_u64_u32 v[18:19], s[16:17], v22, s83, v[6:7]
	v_mad_u64_u32 v[20:21], s[16:17], v17, s83, v[6:7]
	s_add_i32 s14, s10, 16
	s_add_i32 s11, s7, 16
	v_or_b32_e32 v17, s11, v3
	v_or_b32_e32 v22, s14, v2
	s_waitcnt vmcnt(1)
	ds_write_b32 v18, v23
	s_waitcnt vmcnt(0)
	ds_write_b32 v20, v24
	s_sleep 32
	v_or_b32_e32 v20, s14, v0
	v_or_b32_e32 v18, s11, v7
	v_ashrrev_i32_e32 v21, 31, v20
	v_ashrrev_i32_e32 v19, 31, v18
	v_lshlrev_b64 v[20:21], 12, v[20:21]
	v_lshlrev_b64 v[18:19], 12, v[18:19]
	v_lshl_add_u64 v[20:21], v[10:11], 0, v[20:21]
	v_lshl_add_u64 v[18:19], v[10:11], 0, v[18:19]
	global_load_dword v23, v[20:21], off
	global_load_dword v24, v[18:19], off
	v_mad_u64_u32 v[18:19], s[16:17], v22, s83, v[6:7]
	v_mad_u64_u32 v[20:21], s[16:17], v17, s83, v[6:7]
	s_add_i32 s14, s10, 20
	s_add_i32 s11, s7, 20
	v_or_b32_e32 v17, s11, v3
	v_or_b32_e32 v22, s14, v2
	s_waitcnt vmcnt(1)
	ds_write_b32 v18, v23
	s_waitcnt vmcnt(0)
	ds_write_b32 v20, v24
	s_sleep 32
	v_or_b32_e32 v20, s14, v0
	v_or_b32_e32 v18, s11, v7
	v_ashrrev_i32_e32 v21, 31, v20
	v_ashrrev_i32_e32 v19, 31, v18
	v_lshlrev_b64 v[20:21], 12, v[20:21]
	v_lshlrev_b64 v[18:19], 12, v[18:19]
	v_lshl_add_u64 v[20:21], v[10:11], 0, v[20:21]
	v_lshl_add_u64 v[18:19], v[10:11], 0, v[18:19]
	global_load_dword v23, v[20:21], off
	global_load_dword v24, v[18:19], off
	v_mad_u64_u32 v[18:19], s[16:17], v22, s83, v[6:7]
	v_mad_u64_u32 v[20:21], s[16:17], v17, s83, v[6:7]
	s_add_i32 s14, s10, 24
	s_add_i32 s11, s7, 24
	v_or_b32_e32 v17, s11, v3
	v_or_b32_e32 v22, s14, v2
	s_add_i32 s10, s10, 28
	s_add_i32 s7, s7, 28
	s_cmp_lg_u32 s6, 0
	s_waitcnt vmcnt(1)
	ds_write_b32 v18, v23
	s_waitcnt vmcnt(0)
	ds_write_b32 v20, v24
	s_sleep 32
	v_or_b32_e32 v20, s14, v0
	v_or_b32_e32 v18, s11, v7
	v_ashrrev_i32_e32 v21, 31, v20
	v_ashrrev_i32_e32 v19, 31, v18
	v_lshlrev_b64 v[20:21], 12, v[20:21]
	v_lshlrev_b64 v[18:19], 12, v[18:19]
	v_lshl_add_u64 v[20:21], v[10:11], 0, v[20:21]
	v_lshl_add_u64 v[18:19], v[10:11], 0, v[18:19]
	global_load_dword v23, v[20:21], off
	global_load_dword v24, v[18:19], off
	v_mad_u64_u32 v[18:19], s[16:17], v22, s83, v[6:7]
	v_mad_u64_u32 v[20:21], s[16:17], v17, s83, v[6:7]
	v_or_b32_e32 v22, s10, v2
	v_or_b32_e32 v17, s7, v3
	s_waitcnt vmcnt(1)
	ds_write_b32 v18, v23
	s_waitcnt vmcnt(0)
	ds_write_b32 v20, v24
	s_sleep 32
	v_or_b32_e32 v20, s10, v0
	v_or_b32_e32 v18, s7, v7
	v_ashrrev_i32_e32 v21, 31, v20
	v_ashrrev_i32_e32 v19, 31, v18
	v_lshlrev_b64 v[20:21], 12, v[20:21]
	v_lshlrev_b64 v[18:19], 12, v[18:19]
	v_lshl_add_u64 v[20:21], v[10:11], 0, v[20:21]
	v_lshl_add_u64 v[18:19], v[10:11], 0, v[18:19]
	global_load_dword v23, v[20:21], off
	global_load_dword v24, v[18:19], off
	v_mad_u64_u32 v[18:19], s[10:11], v22, s83, v[6:7]
	v_mad_u64_u32 v[20:21], s[10:11], v17, s83, v[6:7]
	s_waitcnt vmcnt(1)
	ds_write_b32 v18, v23
	s_waitcnt vmcnt(0)
	ds_write_b32 v20, v24
	s_sleep 32
	s_cbranch_scc1 .LBB0_824
; #define LAS __attribute__((address_space(3)))
; __device__ __forceinline__ unsigned pkbf(float lo, float hi) { f32x2 v = {lo, hi}; bf16x2v b = __builtin_convertvector(v, bf16x2v); return __builtin_bit_cast(unsigned, b); }
; template <int MODE> __device__ __forceinline__ void transpose_item(const float* W, int K, int N, bf16_t* WT, LAS float* scr, int item, int lane) {
;     ...
;     asm volatile("s_waitcnt lgkmcnt(0)" ::: "memory");
;     const int c = lane & 7;
; #pragma unroll
;     for (int j = 0; j < 4; ++j) {
;         const int n = (lane >> 3) + 8 * j, gn = n0 + n; const LAS float* s = scr + (8 * c) * 33 + n;
;         const int drow = MODE == 0 ? gn : (MODE == 1 ? (gn >= 8608 ? gn + 96 : gn) : (gn < DFF ? 2 * gn : 2 * (gn - DFF) + 1));
;         u32x4 o; o.x = pkbf(s[0 * 33], s[1 * 33]); o.y = pkbf(s[2 * 33], s[3 * 33]); o.z = pkbf(s[4 * 33], s[5 * 33]); o.w = pkbf(s[6 * 33], s[7 * 33]);
;         *(u32x4*)(WT + (size_t)drow * K + k0 + 8 * c) = o;
;     }
;     asm volatile("s_waitcnt lgkmcnt(0)" ::: "memory");
; __device__ __forceinline__ void ph_wconv(CArgs& a, int l, unsigned char* ldsg, int gw, int ngw, int lane, int wv, int mask) {
;     ...
;     if (mask & 4) for (int it = gw; it < I_SQ; it += ngw) transpose_item<0>(a.in[30] + (size_t)l * 1048576, 1024, 1024, (bf16_t*)(ws + WS_WO), scr, it, lane);
	s_waitcnt lgkmcnt(0)
	ds_read2_b32 v[24:25], v13 offset0:33 offset1:41
	ds_read2_b32 v[26:27], v13 offset1:8
	ds_read2_b32 v[28:29], v13 offset0:66 offset1:74
	ds_read2_b32 v[30:31], v13 offset0:99 offset1:107
	ds_read2_b32 v[32:33], v13 offset0:132 offset1:140
	ds_read2_b32 v[34:35], v13 offset0:165 offset1:173
	ds_read2_b32 v[36:37], v13 offset0:198 offset1:206
	ds_read2_b32 v[38:39], v13 offset0:231 offset1:239
	v_or_b32_e32 v22, s42, v12
	s_ashr_i32 s45, s44, 31
	v_ashrrev_i32_e32 v23, 31, v22
	v_lshl_add_u64 v[10:11], s[44:45], 1, v[8:9]
	v_lshlrev_b64 v[22:23], 11, v[22:23]
	s_waitcnt lgkmcnt(6)
	v_cvt_pk_bf16_f32 v18, v26, v24
	s_waitcnt lgkmcnt(4)
	v_cvt_pk_bf16_f32 v19, v28, v30
	s_waitcnt lgkmcnt(2)
	v_cvt_pk_bf16_f32 v20, v32, v34
	s_waitcnt lgkmcnt(0)
	v_cvt_pk_bf16_f32 v21, v36, v38
	v_lshl_add_u64 v[22:23], v[10:11], 0, v[22:23]
	global_store_dwordx4 v[22:23], v[18:21], off
	v_or_b32_e32 v22, s42, v14
	v_ashrrev_i32_e32 v23, 31, v22
	v_lshlrev_b64 v[22:23], 11, v[22:23]
	v_cvt_pk_bf16_f32 v18, v27, v25
	v_cvt_pk_bf16_f32 v19, v29, v31
	v_cvt_pk_bf16_f32 v20, v33, v35
	v_cvt_pk_bf16_f32 v21, v37, v39
	v_lshl_add_u64 v[22:23], v[10:11], 0, v[22:23]
	global_store_dwordx4 v[22:23], v[18:21], off
	ds_read2_b32 v[24:25], v13 offset0:49 offset1:57
	ds_read2_b32 v[26:27], v13 offset0:16 offset1:24
	ds_read2_b32 v[28:29], v13 offset0:82 offset1:90
	ds_read2_b32 v[30:31], v13 offset0:115 offset1:123
	ds_read2_b32 v[32:33], v13 offset0:148 offset1:156
	ds_read2_b32 v[34:35], v13 offset0:181 offset1:189
	ds_read2_b32 v[36:37], v13 offset0:214 offset1:222
	ds_read2_b32 v[38:39], v13 offset0:247 offset1:255
	v_or_b32_e32 v22, s42, v15
	v_ashrrev_i32_e32 v23, 31, v22
	v_lshlrev_b64 v[22:23], 11, v[22:23]
	s_waitcnt lgkmcnt(6)
	v_cvt_pk_bf16_f32 v18, v26, v24
	s_waitcnt lgkmcnt(4)
	v_cvt_pk_bf16_f32 v19, v28, v30
	s_waitcnt lgkmcnt(2)
	v_cvt_pk_bf16_f32 v20, v32, v34
	s_waitcnt lgkmcnt(0)
	v_cvt_pk_bf16_f32 v21, v36, v38
	v_lshl_add_u64 v[22:23], v[10:11], 0, v[22:23]
	global_store_dwordx4 v[22:23], v[18:21], off
	v_or_b32_e32 v22, s42, v16
	v_ashrrev_i32_e32 v23, 31, v22
	v_lshlrev_b64 v[22:23], 11, v[22:23]
	v_cvt_pk_bf16_f32 v18, v27, v25
	v_cvt_pk_bf16_f32 v19, v29, v31
	v_cvt_pk_bf16_f32 v20, v33, v35
	v_cvt_pk_bf16_f32 v21, v37, v39
	v_lshl_add_u64 v[10:11], v[10:11], 0, v[22:23]
	global_store_dwordx4 v[10:11], v[18:21], off
	s_waitcnt lgkmcnt(0)
	s_add_i32 s3, s3, s80
	s_cmpk_lt_i32 s3, 0x200
	s_cbranch_scc1 .LBB0_823

; template <int MODE> __device__ __forceinline__ void transpose_item(const float* W, int K, int N, bf16_t* WT, LAS float* scr, int item, int lane) {
;     const int nblk = N / 32, kb = item / nblk, nb = item % nblk, k0 = 64 * kb, n0 = 32 * nb;
; #pragma unroll 8
;     for (int i = 0; i < 32; ++i) { const int kk = 2 * i + (lane >> 5); scr[kk * 33 + (lane & 31)] = W[(size_t)(k0 + kk) * N + n0 + (lane & 31)]; }
.LBB0_829:
	s_lshl_b32 s7, s4, 1
	s_lshl_b32 s6, s3, 1
	v_or_b32_e32 v18, s7, v0
	v_or_b32_e32 v20, s6, v7
	v_mad_i64_i32 v[18:19], s[10:11], v18, s31, v[10:11]
	v_mad_i64_i32 v[20:21], s[10:11], v20, s31, v[10:11]
	global_load_dword v23, v[18:19], off
	global_load_dword v24, v[20:21], off
	v_or_b32_e32 v17, s6, v3
	v_or_b32_e32 v22, s7, v2
	v_mad_u64_u32 v[18:19], s[10:11], v22, s83, v[6:7]
	v_mad_u64_u32 v[20:21], s[10:11], v17, s83, v[6:7]
	s_add_i32 s11, s7, 4
	s_add_i32 s10, s6, 4
	v_or_b32_e32 v17, s10, v3
	v_or_b32_e32 v22, s11, v2
	s_add_i32 s4, s4, 16
	s_add_i32 s3, s3, 16
	s_add_i32 s5, s5, -16
	s_waitcnt vmcnt(1)
	ds_write_b32 v18, v23
	s_waitcnt vmcnt(0)
	ds_write_b32 v20, v24
	s_sleep 32
	v_or_b32_e32 v18, s11, v0
	v_or_b32_e32 v20, s10, v7
	v_mad_i64_i32 v[18:19], s[10:11], v18, s31, v[10:11]
	v_mad_i64_i32 v[20:21], s[10:11], v20, s31, v[10:11]
	global_load_dword v23, v[18:19], off
	global_load_dword v24, v[20:21], off
	v_mad_u64_u32 v[18:19], s[10:11], v22, s83, v[6:7]
	v_mad_u64_u32 v[20:21], s[10:11], v17, s83, v[6:7]
	s_add_i32 s11, s7, 8
	s_add_i32 s10, s6, 8
	v_or_b32_e32 v17, s10, v3
	v_or_b32_e32 v22, s11, v2
	s_waitcnt vmcnt(1)
	ds_write_b32 v18, v23
	s_waitcnt vmcnt(0)
	ds_write_b32 v20, v24
	s_sleep 32
	v_or_b32_e32 v18, s11, v0
	v_or_b32_e32 v20, s10, v7
	v_mad_i64_i32 v[18:19], s[10:11], v18, s31, v[10:11]
	v_mad_i64_i32 v[20:21], s[10:11], v20, s31, v[10:11]
	global_load_dword v23, v[18:19], off
	global_load_dword v24, v[20:21], off
	v_mad_u64_u32 v[18:19], s[10:11], v22, s83, v[6:7]
	v_mad_u64_u32 v[20:21], s[10:11], v17, s83, v[6:7]
	s_add_i32 s11, s7, 12
	s_add_i32 s10, s6, 12
	v_or_b32_e32 v17, s10, v3
	v_or_b32_e32 v22, s11, v2
	s_waitcnt vmcnt(1)
	ds_write_b32 v18, v23
	s_waitcnt vmcnt(0)
	ds_write_b32 v20, v24
	s_sleep 32
	v_or_b32_e32 v18, s11, v0
	v_or_b32_e32 v20, s10, v7
	v_mad_i64_i32 v[18:19], s[10:11], v18, s31, v[10:11]
	v_mad_i64_i32 v[20:21], s[10:11], v20, s31, v[10:11]
	global_load_dword v23, v[18:19], off
	global_load_dword v24, v[20:21], off
	v_mad_u64_u32 v[18:19], s[10:11], v22, s83, v[6:7]
	v_mad_u64_u32 v[20:21], s[10:11], v17, s83, v[6:7]
	s_add_i32 s11, s7, 16
	s_add_i32 s10, s6, 16
	v_or_b32_e32 v17, s10, v3
	v_or_b32_e32 v22, s11, v2
	s_waitcnt vmcnt(1)
	ds_write_b32 v18, v23
	s_waitcnt vmcnt(0)
	ds_write_b32 v20, v24
	s_sleep 32
	v_or_b32_e32 v18, s11, v0
	v_or_b32_e32 v20, s10, v7
	v_mad_i64_i32 v[18:19], s[10:11], v18, s31, v[10:11]
	v_mad_i64_i32 v[20:21], s[10:11], v20, s31, v[10:11]
	global_load_dword v23, v[18:19], off
	global_load_dword v24, v[20:21], off
	v_mad_u64_u32 v[18:19], s[10:11], v22, s83, v[6:7]
	v_mad_u64_u32 v[20:21], s[10:11], v17, s83, v[6:7]
	s_add_i32 s11, s7, 20
	s_add_i32 s10, s6, 20
	v_or_b32_e32 v17, s10, v3
	v_or_b32_e32 v22, s11, v2
	s_waitcnt vmcnt(1)
	ds_write_b32 v18, v23
	s_waitcnt vmcnt(0)
	ds_write_b32 v20, v24
	s_sleep 32
	v_or_b32_e32 v18, s11, v0
	v_or_b32_e32 v20, s10, v7
	v_mad_i64_i32 v[18:19], s[10:11], v18, s31, v[10:11]
	v_mad_i64_i32 v[20:21], s[10:11], v20, s31, v[10:11]
	global_load_dword v23, v[18:19], off
	global_load_dword v24, v[20:21], off
	v_mad_u64_u32 v[18:19], s[10:11], v22, s83, v[6:7]
	v_mad_u64_u32 v[20:21], s[10:11], v17, s83, v[6:7]
	s_add_i32 s11, s7, 24
	s_add_i32 s10, s6, 24
	v_or_b32_e32 v17, s10, v3
	v_or_b32_e32 v22, s11, v2
	s_add_i32 s7, s7, 28
	s_add_i32 s6, s6, 28
	s_cmp_lg_u32 s5, 0
	s_waitcnt vmcnt(1)
	ds_write_b32 v18, v23
	s_waitcnt vmcnt(0)
	ds_write_b32 v20, v24
	s_sleep 32
	v_or_b32_e32 v18, s11, v0
	v_or_b32_e32 v20, s10, v7
	v_mad_i64_i32 v[18:19], s[10:11], v18, s31, v[10:11]
	v_mad_i64_i32 v[20:21], s[10:11], v20, s31, v[10:11]
	global_load_dword v23, v[18:19], off
	global_load_dword v24, v[20:21], off
	v_mad_u64_u32 v[18:19], s[10:11], v22, s83, v[6:7]
	v_mad_u64_u32 v[20:21], s[10:11], v17, s83, v[6:7]
	v_or_b32_e32 v17, s6, v3
	v_or_b32_e32 v22, s7, v2
	s_waitcnt vmcnt(1)
	ds_write_b32 v18, v23
	s_waitcnt vmcnt(0)
	ds_write_b32 v20, v24
	s_sleep 32
	v_or_b32_e32 v18, s7, v0
	v_or_b32_e32 v20, s6, v7
	v_mad_i64_i32 v[18:19], s[6:7], v18, s31, v[10:11]
	v_mad_i64_i32 v[20:21], s[6:7], v20, s31, v[10:11]
	global_load_dword v23, v[18:19], off
	global_load_dword v24, v[20:21], off
	v_mad_u64_u32 v[18:19], s[6:7], v22, s83, v[6:7]
	v_mad_u64_u32 v[20:21], s[6:7], v17, s83, v[6:7]
	s_waitcnt vmcnt(1)
	ds_write_b32 v18, v23
	s_waitcnt vmcnt(0)
	ds_write_b32 v20, v24
	s_sleep 32
	s_cbranch_scc1 .LBB0_829
; #define LAS __attribute__((address_space(3)))
; __device__ __forceinline__ unsigned pkbf(float lo, float hi) { f32x2 v = {lo, hi}; bf16x2v b = __builtin_convertvector(v, bf16x2v); return __builtin_bit_cast(unsigned, b); }
; template <int MODE> __device__ __forceinline__ void transpose_item(const float* W, int K, int N, bf16_t* WT, LAS float* scr, int item, int lane) {
;     ...
;     asm volatile("s_waitcnt lgkmcnt(0)" ::: "memory");
;     const int c = lane & 7;
; #pragma unroll
;     for (int j = 0; j < 4; ++j) {
;         const int n = (lane >> 3) + 8 * j, gn = n0 + n; const LAS float* s = scr + (8 * c) * 33 + n;
;         const int drow = MODE == 0 ? gn : (MODE == 1 ? (gn >= 8608 ? gn + 96 : gn) : (gn < DFF ? 2 * gn : 2 * (gn - DFF) + 1));
;         u32x4 o; o.x = pkbf(s[0 * 33], s[1 * 33]); o.y = pkbf(s[2 * 33], s[3 * 33]); o.z = pkbf(s[4 * 33], s[5 * 33]); o.w = pkbf(s[6 * 33], s[7 * 33]);
;         *(u32x4*)(WT + (size_t)drow * K + k0 + 8 * c) = o;
;     }
;     asm volatile("s_waitcnt lgkmcnt(0)" ::: "memory");
; __device__ __forceinline__ void ph_wconv(CArgs& a, int l, unsigned char* ldsg, int gw, int ngw, int lane, int wv, int mask) {
;     ...
;     if (mask & 8) for (int it = gw; it < I_WI; it += ngw) transpose_item<2>(a.in[31] + (size_t)l * 1024 * 5632, 1024, 5632, (bf16_t*)(ws + WS_WI), scr, it, lane);
	s_waitcnt lgkmcnt(0)
	v_or_b32_e32 v0, s40, v12
	v_cmp_gt_i32_e32 vcc, s30, v0
	v_lshlrev_b32_e32 v0, 1, v0
	ds_read2_b32 v[24:25], v13 offset0:33 offset1:41
	ds_read2_b32 v[26:27], v13 offset1:8
	ds_read2_b32 v[28:29], v13 offset0:66 offset1:74
	ds_read2_b32 v[30:31], v13 offset0:99 offset1:107
	ds_read2_b32 v[32:33], v13 offset0:132 offset1:140
	ds_read2_b32 v[34:35], v13 offset0:165 offset1:173
	ds_read2_b32 v[36:37], v13 offset0:198 offset1:206
	ds_read2_b32 v[38:39], v13 offset0:231 offset1:239
	v_add_u32_e32 v7, 0xffffea01, v0
	v_cndmask_b32_e32 v22, v7, v0, vcc
	s_ashr_i32 s43, s42, 31
	v_ashrrev_i32_e32 v23, 31, v22
	v_or_b32_e32 v0, s40, v14
	v_lshl_add_u64 v[10:11], s[42:43], 1, v[8:9]
	v_lshlrev_b64 v[22:23], 11, v[22:23]
	v_cmp_gt_i32_e32 vcc, s30, v0
	v_lshlrev_b32_e32 v0, 1, v0
	s_waitcnt lgkmcnt(6)
	v_cvt_pk_bf16_f32 v18, v26, v24
	s_waitcnt lgkmcnt(4)
	v_cvt_pk_bf16_f32 v19, v28, v30
	s_waitcnt lgkmcnt(2)
	v_cvt_pk_bf16_f32 v20, v32, v34
	s_waitcnt lgkmcnt(0)
	v_cvt_pk_bf16_f32 v21, v36, v38
	v_lshl_add_u64 v[22:23], v[10:11], 0, v[22:23]
	v_add_u32_e32 v7, 0xffffea01, v0
	global_store_dwordx4 v[22:23], v[18:21], off
	v_cndmask_b32_e32 v22, v7, v0, vcc
	v_ashrrev_i32_e32 v23, 31, v22
	v_lshlrev_b64 v[22:23], 11, v[22:23]
	v_cvt_pk_bf16_f32 v18, v27, v25
	v_cvt_pk_bf16_f32 v19, v29, v31
	v_cvt_pk_bf16_f32 v20, v33, v35
	v_cvt_pk_bf16_f32 v21, v37, v39
	v_lshl_add_u64 v[22:23], v[10:11], 0, v[22:23]
	global_store_dwordx4 v[22:23], v[18:21], off
	v_or_b32_e32 v0, s40, v15
	v_cmp_gt_i32_e32 vcc, s30, v0
	v_lshlrev_b32_e32 v0, 1, v0
	ds_read2_b32 v[24:25], v13 offset0:49 offset1:57
	ds_read2_b32 v[26:27], v13 offset0:16 offset1:24
	ds_read2_b32 v[28:29], v13 offset0:82 offset1:90
	ds_read2_b32 v[30:31], v13 offset0:115 offset1:123
	ds_read2_b32 v[32:33], v13 offset0:148 offset1:156
	ds_read2_b32 v[34:35], v13 offset0:181 offset1:189
	ds_read2_b32 v[36:37], v13 offset0:214 offset1:222
	ds_read2_b32 v[38:39], v13 offset0:247 offset1:255
	v_add_u32_e32 v7, 0xffffea01, v0
	v_cndmask_b32_e32 v22, v7, v0, vcc
	v_ashrrev_i32_e32 v23, 31, v22
	v_or_b32_e32 v0, s40, v16
	v_lshlrev_b64 v[22:23], 11, v[22:23]
	v_cmp_gt_i32_e32 vcc, s30, v0
	v_lshlrev_b32_e32 v0, 1, v0
	s_waitcnt lgkmcnt(6)
	v_cvt_pk_bf16_f32 v18, v26, v24
	s_waitcnt lgkmcnt(4)
	v_cvt_pk_bf16_f32 v19, v28, v30
	s_waitcnt lgkmcnt(2)
	v_cvt_pk_bf16_f32 v20, v32, v34
	s_waitcnt lgkmcnt(0)
	v_cvt_pk_bf16_f32 v21, v36, v38
	v_lshl_add_u64 v[22:23], v[10:11], 0, v[22:23]
	v_add_u32_e32 v7, 0xffffea01, v0
	global_store_dwordx4 v[22:23], v[18:21], off
	v_cndmask_b32_e32 v22, v7, v0, vcc
	v_ashrrev_i32_e32 v23, 31, v22
	v_lshlrev_b64 v[22:23], 11, v[22:23]
	v_cvt_pk_bf16_f32 v18, v27, v25
	v_cvt_pk_bf16_f32 v19, v29, v31
	v_cvt_pk_bf16_f32 v20, v33, v35
	v_cvt_pk_bf16_f32 v21, v37, v39
	v_lshl_add_u64 v[10:11], v[10:11], 0, v[22:23]
	global_store_dwordx4 v[10:11], v[18:21], off
	s_waitcnt lgkmcnt(0)
	s_add_i32 s1, s1, s80
	s_cmpk_gt_i32 s1, 0xaff
	s_cbranch_scc0 .LBB0_828

; template <int MODE> __device__ __forceinline__ void transpose_item(const float* W, int K, int N, bf16_t* WT, LAS float* scr, int item, int lane) {
;     const int nblk = N / 32, kb = item / nblk, nb = item % nblk, k0 = 64 * kb, n0 = 32 * nb;
; #pragma unroll 8
;     for (int i = 0; i < 32; ++i) { const int kk = 2 * i + (lane >> 5); scr[kk * 33 + (lane & 31)] = W[(size_t)(k0 + kk) * N + n0 + (lane & 31)]; }
.LBB0_836:
	s_lshl_b32 s14, s7, 1
	s_lshl_b32 s11, s6, 1
	v_or_b32_e32 v20, s14, v0
	v_or_b32_e32 v18, s11, v7
	v_ashrrev_i32_e32 v21, 31, v20
	v_ashrrev_i32_e32 v19, 31, v18
	v_lshlrev_b64 v[20:21], 12, v[20:21]
	v_lshlrev_b64 v[18:19], 12, v[18:19]
	v_lshl_add_u64 v[20:21], v[10:11], 0, v[20:21]
	v_lshl_add_u64 v[18:19], v[10:11], 0, v[18:19]
	global_load_dword v23, v[20:21], off
	global_load_dword v24, v[18:19], off
	v_or_b32_e32 v17, s11, v3
	v_or_b32_e32 v22, s14, v2
	v_mad_u64_u32 v[18:19], s[16:17], v22, s83, v[6:7]
	v_mad_u64_u32 v[20:21], s[16:17], v17, s83, v[6:7]
	s_add_i32 s17, s14, 4
	s_add_i32 s16, s11, 4
	v_or_b32_e32 v17, s16, v3
	v_or_b32_e32 v22, s17, v2
	s_add_i32 s7, s7, 16
	s_add_i32 s6, s6, 16
	s_add_i32 s10, s10, -16
	s_waitcnt vmcnt(1)
	ds_write_b32 v18, v23
	s_waitcnt vmcnt(0)
	ds_write_b32 v20, v24
	s_sleep 32
	v_or_b32_e32 v20, s17, v0
	v_or_b32_e32 v18, s16, v7
	v_ashrrev_i32_e32 v21, 31, v20
	v_ashrrev_i32_e32 v19, 31, v18
	v_lshlrev_b64 v[20:21], 12, v[20:21]
	v_lshlrev_b64 v[18:19], 12, v[18:19]
	v_lshl_add_u64 v[20:21], v[10:11], 0, v[20:21]
	v_lshl_add_u64 v[18:19], v[10:11], 0, v[18:19]
	global_load_dword v23, v[20:21], off
	global_load_dword v24, v[18:19], off
	v_mad_u64_u32 v[18:19], s[16:17], v22, s83, v[6:7]
	v_mad_u64_u32 v[20:21], s[16:17], v17, s83, v[6:7]
	s_add_i32 s17, s14, 8
	s_add_i32 s16, s11, 8
	v_or_b32_e32 v17, s16, v3
	v_or_b32_e32 v22, s17, v2
	s_waitcnt vmcnt(1)
	ds_write_b32 v18, v23
	s_waitcnt vmcnt(0)
	ds_write_b32 v20, v24
	s_sleep 32
	v_or_b32_e32 v20, s17, v0
	v_or_b32_e32 v18, s16, v7
	v_ashrrev_i32_e32 v21, 31, v20
	v_ashrrev_i32_e32 v19, 31, v18
	v_lshlrev_b64 v[20:21], 12, v[20:21]
	v_lshlrev_b64 v[18:19], 12, v[18:19]
	v_lshl_add_u64 v[20:21], v[10:11], 0, v[20:21]
	v_lshl_add_u64 v[18:19], v[10:11], 0, v[18:19]
	global_load_dword v23, v[20:21], off
	global_load_dword v24, v[18:19], off
	v_mad_u64_u32 v[18:19], s[16:17], v22, s83, v[6:7]
	v_mad_u64_u32 v[20:21], s[16:17], v17, s83, v[6:7]
	s_add_i32 s17, s14, 12
	s_add_i32 s16, s11, 12
	v_or_b32_e32 v17, s16, v3
	v_or_b32_e32 v22, s17, v2
	s_waitcnt vmcnt(1)
	ds_write_b32 v18, v23
	s_waitcnt vmcnt(0)
	ds_write_b32 v20, v24
	s_sleep 32
	v_or_b32_e32 v20, s17, v0
	v_or_b32_e32 v18, s16, v7
	v_ashrrev_i32_e32 v21, 31, v20
	v_ashrrev_i32_e32 v19, 31, v18
	v_lshlrev_b64 v[20:21], 12, v[20:21]
	v_lshlrev_b64 v[18:19], 12, v[18:19]
	v_lshl_add_u64 v[20:21], v[10:11], 0, v[20:21]
	v_lshl_add_u64 v[18:19], v[10:11], 0, v[18:19]
	global_load_dword v23, v[20:21], off
	global_load_dword v24, v[18:19], off
	v_mad_u64_u32 v[18:19], s[16:17], v22, s83, v[6:7]
	v_mad_u64_u32 v[20:21], s[16:17], v17, s83, v[6:7]
	s_add_i32 s17, s14, 16
	s_add_i32 s16, s11, 16
	v_or_b32_e32 v17, s16, v3
	v_or_b32_e32 v22, s17, v2
	s_waitcnt vmcnt(1)
	ds_write_b32 v18, v23
	s_waitcnt vmcnt(0)
	ds_write_b32 v20, v24
	s_sleep 32
	v_or_b32_e32 v20, s17, v0
	v_or_b32_e32 v18, s16, v7
	v_ashrrev_i32_e32 v21, 31, v20
	v_ashrrev_i32_e32 v19, 31, v18
	v_lshlrev_b64 v[20:21], 12, v[20:21]
	v_lshlrev_b64 v[18:19], 12, v[18:19]
	v_lshl_add_u64 v[20:21], v[10:11], 0, v[20:21]
	v_lshl_add_u64 v[18:19], v[10:11], 0, v[18:19]
	global_load_dword v23, v[20:21], off
	global_load_dword v24, v[18:19], off
	v_mad_u64_u32 v[18:19], s[16:17], v22, s83, v[6:7]
	v_mad_u64_u32 v[20:21], s[16:17], v17, s83, v[6:7]
	s_add_i32 s17, s14, 20
	s_add_i32 s16, s11, 20
	v_or_b32_e32 v17, s16, v3
	v_or_b32_e32 v22, s17, v2
	s_waitcnt vmcnt(1)
	ds_write_b32 v18, v23
	s_waitcnt vmcnt(0)
	ds_write_b32 v20, v24
	s_sleep 32
	v_or_b32_e32 v20, s17, v0
	v_or_b32_e32 v18, s16, v7
	v_ashrrev_i32_e32 v21, 31, v20
	v_ashrrev_i32_e32 v19, 31, v18
	v_lshlrev_b64 v[20:21], 12, v[20:21]
	v_lshlrev_b64 v[18:19], 12, v[18:19]
	v_lshl_add_u64 v[20:21], v[10:11], 0, v[20:21]
	v_lshl_add_u64 v[18:19], v[10:11], 0, v[18:19]
	global_load_dword v23, v[20:21], off
	global_load_dword v24, v[18:19], off
	v_mad_u64_u32 v[18:19], s[16:17], v22, s83, v[6:7]
	v_mad_u64_u32 v[20:21], s[16:17], v17, s83, v[6:7]
	s_add_i32 s17, s14, 24
	s_add_i32 s16, s11, 24
	v_or_b32_e32 v17, s16, v3
	v_or_b32_e32 v22, s17, v2
	s_add_i32 s14, s14, 28
	s_add_i32 s11, s11, 28
	s_cmp_lg_u32 s10, 0
	s_waitcnt vmcnt(1)
	ds_write_b32 v18, v23
	s_waitcnt vmcnt(0)
	ds_write_b32 v20, v24
	s_sleep 32
	v_or_b32_e32 v20, s17, v0
	v_or_b32_e32 v18, s16, v7
	v_ashrrev_i32_e32 v21, 31, v20
	v_ashrrev_i32_e32 v19, 31, v18
	v_lshlrev_b64 v[20:21], 12, v[20:21]
	v_lshlrev_b64 v[18:19], 12, v[18:19]
	v_lshl_add_u64 v[20:21], v[10:11], 0, v[20:21]
	v_lshl_add_u64 v[18:19], v[10:11], 0, v[18:19]
	global_load_dword v23, v[20:21], off
	global_load_dword v24, v[18:19], off
	v_mad_u64_u32 v[18:19], s[16:17], v22, s83, v[6:7]
	v_mad_u64_u32 v[20:21], s[16:17], v17, s83, v[6:7]
	v_or_b32_e32 v22, s14, v2
	v_or_b32_e32 v17, s11, v3
	s_waitcnt vmcnt(1)
	ds_write_b32 v18, v23
	s_waitcnt vmcnt(0)
	ds_write_b32 v20, v24
	s_sleep 32
	v_or_b32_e32 v20, s14, v0
	v_or_b32_e32 v18, s11, v7
	v_ashrrev_i32_e32 v21, 31, v20
	v_ashrrev_i32_e32 v19, 31, v18
	v_lshlrev_b64 v[20:21], 12, v[20:21]
	v_lshlrev_b64 v[18:19], 12, v[18:19]
	v_lshl_add_u64 v[20:21], v[10:11], 0, v[20:21]
	v_lshl_add_u64 v[18:19], v[10:11], 0, v[18:19]
	global_load_dword v23, v[20:21], off
	global_load_dword v24, v[18:19], off
	v_mad_u64_u32 v[18:19], s[16:17], v22, s83, v[6:7]
	v_mad_u64_u32 v[20:21], s[16:17], v17, s83, v[6:7]
	s_waitcnt vmcnt(1)
	ds_write_b32 v18, v23
	s_waitcnt vmcnt(0)
	ds_write_b32 v20, v24
	s_sleep 32
	s_cbranch_scc1 .LBB0_836
; #define LAS __attribute__((address_space(3)))
; __device__ __forceinline__ unsigned pkbf(float lo, float hi) { f32x2 v = {lo, hi}; bf16x2v b = __builtin_convertvector(v, bf16x2v); return __builtin_bit_cast(unsigned, b); }
; template <int MODE> __device__ __forceinline__ void transpose_item(const float* W, int K, int N, bf16_t* WT, LAS float* scr, int item, int lane) {
;     ...
;     asm volatile("s_waitcnt lgkmcnt(0)" ::: "memory");
;     const int c = lane & 7;
; #pragma unroll
;     for (int j = 0; j < 4; ++j) {
;         const int n = (lane >> 3) + 8 * j, gn = n0 + n; const LAS float* s = scr + (8 * c) * 33 + n;
;         const int drow = MODE == 0 ? gn : (MODE == 1 ? (gn >= 8608 ? gn + 96 : gn) : (gn < DFF ? 2 * gn : 2 * (gn - DFF) + 1));
;         u32x4 o; o.x = pkbf(s[0 * 33], s[1 * 33]); o.y = pkbf(s[2 * 33], s[3 * 33]); o.z = pkbf(s[4 * 33], s[5 * 33]); o.w = pkbf(s[6 * 33], s[7 * 33]);
;         *(u32x4*)(WT + (size_t)drow * K + k0 + 8 * c) = o;
;     }
;     asm volatile("s_waitcnt lgkmcnt(0)" ::: "memory");
; __device__ __forceinline__ void ph_wconv(CArgs& a, int l, unsigned char* ldsg, int gw, int ngw, int lane, int wv, int mask) {
;     ...
;     if (mask & 4) for (int it = gw; it < I_SQ; it += ngw) transpose_item<0>(a.in[30] + (size_t)l * 1048576, 1024, 1024, (bf16_t*)(ws + WS_WO), scr, it, lane);
	s_waitcnt lgkmcnt(0)
	ds_read2_b32 v[24:25], v13 offset0:33 offset1:41
	ds_read2_b32 v[26:27], v13 offset1:8
	ds_read2_b32 v[28:29], v13 offset0:66 offset1:74
	ds_read2_b32 v[30:31], v13 offset0:99 offset1:107
	ds_read2_b32 v[32:33], v13 offset0:132 offset1:140
	ds_read2_b32 v[34:35], v13 offset0:165 offset1:173
	ds_read2_b32 v[36:37], v13 offset0:198 offset1:206
	ds_read2_b32 v[38:39], v13 offset0:231 offset1:239
	v_or_b32_e32 v22, s42, v12
	s_ashr_i32 s45, s44, 31
	v_ashrrev_i32_e32 v23, 31, v22
	v_lshl_add_u64 v[10:11], s[44:45], 1, v[8:9]
	v_lshlrev_b64 v[22:23], 11, v[22:23]
	s_waitcnt lgkmcnt(6)
	v_cvt_pk_bf16_f32 v18, v26, v24
	s_waitcnt lgkmcnt(4)
	v_cvt_pk_bf16_f32 v19, v28, v30
	s_waitcnt lgkmcnt(2)
	v_cvt_pk_bf16_f32 v20, v32, v34
	s_waitcnt lgkmcnt(0)
	v_cvt_pk_bf16_f32 v21, v36, v38
	v_lshl_add_u64 v[22:23], v[10:11], 0, v[22:23]
	global_store_dwordx4 v[22:23], v[18:21], off
	v_or_b32_e32 v22, s42, v14
	v_ashrrev_i32_e32 v23, 31, v22
	v_lshlrev_b64 v[22:23], 11, v[22:23]
	v_cvt_pk_bf16_f32 v18, v27, v25
	v_cvt_pk_bf16_f32 v19, v29, v31
	v_cvt_pk_bf16_f32 v20, v33, v35
	v_cvt_pk_bf16_f32 v21, v37, v39
	v_lshl_add_u64 v[22:23], v[10:11], 0, v[22:23]
	global_store_dwordx4 v[22:23], v[18:21], off
	ds_read2_b32 v[24:25], v13 offset0:49 offset1:57
	ds_read2_b32 v[26:27], v13 offset0:16 offset1:24
	ds_read2_b32 v[28:29], v13 offset0:82 offset1:90
	ds_read2_b32 v[30:31], v13 offset0:115 offset1:123
	ds_read2_b32 v[32:33], v13 offset0:148 offset1:156
	ds_read2_b32 v[34:35], v13 offset0:181 offset1:189
	ds_read2_b32 v[36:37], v13 offset0:214 offset1:222
	ds_read2_b32 v[38:39], v13 offset0:247 offset1:255
	v_or_b32_e32 v22, s42, v15
	v_ashrrev_i32_e32 v23, 31, v22
	v_lshlrev_b64 v[22:23], 11, v[22:23]
	s_waitcnt lgkmcnt(6)
	v_cvt_pk_bf16_f32 v18, v26, v24
	s_waitcnt lgkmcnt(4)
	v_cvt_pk_bf16_f32 v19, v28, v30
	s_waitcnt lgkmcnt(2)
	v_cvt_pk_bf16_f32 v20, v32, v34
	s_waitcnt lgkmcnt(0)
	v_cvt_pk_bf16_f32 v21, v36, v38
	v_lshl_add_u64 v[22:23], v[10:11], 0, v[22:23]
	global_store_dwordx4 v[22:23], v[18:21], off
	v_or_b32_e32 v22, s42, v16
	v_ashrrev_i32_e32 v23, 31, v22
	v_lshlrev_b64 v[22:23], 11, v[22:23]
	v_cvt_pk_bf16_f32 v18, v27, v25
	v_cvt_pk_bf16_f32 v19, v29, v31
	v_cvt_pk_bf16_f32 v20, v33, v35
	v_cvt_pk_bf16_f32 v21, v37, v39
	v_lshl_add_u64 v[10:11], v[10:11], 0, v[22:23]
	global_store_dwordx4 v[10:11], v[18:21], off
	s_waitcnt lgkmcnt(0)
	s_add_i32 s5, s5, s3
	s_cmpk_lt_i32 s5, 0x200
	s_cbranch_scc1 .LBB0_835

; template <int MODE> __device__ __forceinline__ void transpose_item(const float* W, int K, int N, bf16_t* WT, LAS float* scr, int item, int lane) {
;     const int nblk = N / 32, kb = item / nblk, nb = item % nblk, k0 = 64 * kb, n0 = 32 * nb;
; #pragma unroll 8
;     for (int i = 0; i < 32; ++i) { const int kk = 2 * i + (lane >> 5); scr[kk * 33 + (lane & 31)] = W[(size_t)(k0 + kk) * N + n0 + (lane & 31)]; }
.LBB0_841:
	s_lshl_b32 s10, s5, 1
	s_lshl_b32 s7, s4, 1
	v_or_b32_e32 v18, s10, v0
	v_or_b32_e32 v20, s7, v7
	v_mad_i64_i32 v[18:19], s[16:17], v18, s31, v[10:11]
	v_mad_i64_i32 v[20:21], s[16:17], v20, s31, v[10:11]
	global_load_dword v23, v[18:19], off
	global_load_dword v24, v[20:21], off
	v_or_b32_e32 v22, s10, v2
	v_or_b32_e32 v17, s7, v3
	v_mad_u64_u32 v[18:19], s[16:17], v22, s83, v[6:7]
	s_add_i32 s14, s10, 4
	v_mad_u64_u32 v[20:21], s[16:17], v17, s83, v[6:7]
	s_add_i32 s11, s7, 4
	v_or_b32_e32 v22, s14, v2
	v_or_b32_e32 v17, s11, v3
	s_add_i32 s5, s5, 16
	s_add_i32 s4, s4, 16
	s_add_i32 s6, s6, -16
	s_waitcnt vmcnt(1)
	ds_write_b32 v18, v23
	s_waitcnt vmcnt(0)
	ds_write_b32 v20, v24
	s_sleep 32
	v_or_b32_e32 v18, s14, v0
	v_or_b32_e32 v20, s11, v7
	v_mad_i64_i32 v[18:19], s[16:17], v18, s31, v[10:11]
	v_mad_i64_i32 v[20:21], s[16:17], v20, s31, v[10:11]
	global_load_dword v23, v[18:19], off
	global_load_dword v24, v[20:21], off
	v_mad_u64_u32 v[18:19], s[16:17], v22, s83, v[6:7]
	s_add_i32 s14, s10, 8
	v_mad_u64_u32 v[20:21], s[16:17], v17, s83, v[6:7]
	s_add_i32 s11, s7, 8
	v_or_b32_e32 v22, s14, v2
	v_or_b32_e32 v17, s11, v3
	s_waitcnt vmcnt(1)
	ds_write_b32 v18, v23
	s_waitcnt vmcnt(0)
	ds_write_b32 v20, v24
	s_sleep 32
	v_or_b32_e32 v18, s14, v0
	v_or_b32_e32 v20, s11, v7
	v_mad_i64_i32 v[18:19], s[16:17], v18, s31, v[10:11]
	v_mad_i64_i32 v[20:21], s[16:17], v20, s31, v[10:11]
	global_load_dword v23, v[18:19], off
	global_load_dword v24, v[20:21], off
	v_mad_u64_u32 v[18:19], s[16:17], v22, s83, v[6:7]
	s_add_i32 s14, s10, 12
	v_mad_u64_u32 v[20:21], s[16:17], v17, s83, v[6:7]
	s_add_i32 s11, s7, 12
	v_or_b32_e32 v22, s14, v2
	v_or_b32_e32 v17, s11, v3
	s_waitcnt vmcnt(1)
	ds_write_b32 v18, v23
	s_waitcnt vmcnt(0)
	ds_write_b32 v20, v24
	s_sleep 32
	v_or_b32_e32 v18, s14, v0
	v_or_b32_e32 v20, s11, v7
	v_mad_i64_i32 v[18:19], s[16:17], v18, s31, v[10:11]
	v_mad_i64_i32 v[20:21], s[16:17], v20, s31, v[10:11]
	global_load_dword v23, v[18:19], off
	global_load_dword v24, v[20:21], off
	v_mad_u64_u32 v[18:19], s[16:17], v22, s83, v[6:7]
	s_add_i32 s14, s10, 16
	v_mad_u64_u32 v[20:21], s[16:17], v17, s83, v[6:7]
	s_add_i32 s11, s7, 16
	v_or_b32_e32 v22, s14, v2
	v_or_b32_e32 v17, s11, v3
	s_waitcnt vmcnt(1)
	ds_write_b32 v18, v23
	s_waitcnt vmcnt(0)
	ds_write_b32 v20, v24
	s_sleep 32
	v_or_b32_e32 v18, s14, v0
	v_or_b32_e32 v20, s11, v7
	v_mad_i64_i32 v[18:19], s[16:17], v18, s31, v[10:11]
	v_mad_i64_i32 v[20:21], s[16:17], v20, s31, v[10:11]
	global_load_dword v23, v[18:19], off
	global_load_dword v24, v[20:21], off
	v_mad_u64_u32 v[18:19], s[16:17], v22, s83, v[6:7]
	s_add_i32 s14, s10, 20
	v_mad_u64_u32 v[20:21], s[16:17], v17, s83, v[6:7]
	s_add_i32 s11, s7, 20
	v_or_b32_e32 v22, s14, v2
	v_or_b32_e32 v17, s11, v3
	s_waitcnt vmcnt(1)
	ds_write_b32 v18, v23
	s_waitcnt vmcnt(0)
	ds_write_b32 v20, v24
	s_sleep 32
	v_or_b32_e32 v18, s14, v0
	v_or_b32_e32 v20, s11, v7
	v_mad_i64_i32 v[18:19], s[16:17], v18, s31, v[10:11]
	v_mad_i64_i32 v[20:21], s[16:17], v20, s31, v[10:11]
	global_load_dword v23, v[18:19], off
	global_load_dword v24, v[20:21], off
	v_mad_u64_u32 v[18:19], s[16:17], v22, s83, v[6:7]
	s_add_i32 s14, s10, 24
	v_mad_u64_u32 v[20:21], s[16:17], v17, s83, v[6:7]
	s_add_i32 s11, s7, 24
	v_or_b32_e32 v22, s14, v2
	v_or_b32_e32 v17, s11, v3
	s_add_i32 s10, s10, 28
	s_add_i32 s7, s7, 28
	s_cmp_lg_u32 s6, 0
	s_waitcnt vmcnt(1)
	ds_write_b32 v18, v23
	s_waitcnt vmcnt(0)
	ds_write_b32 v20, v24
	s_sleep 32
	v_or_b32_e32 v18, s14, v0
	v_or_b32_e32 v20, s11, v7
	v_mad_i64_i32 v[18:19], s[16:17], v18, s31, v[10:11]
	v_mad_i64_i32 v[20:21], s[16:17], v20, s31, v[10:11]
	global_load_dword v23, v[18:19], off
	global_load_dword v24, v[20:21], off
	v_mad_u64_u32 v[18:19], s[16:17], v22, s83, v[6:7]
	v_mad_u64_u32 v[20:21], s[16:17], v17, s83, v[6:7]
	v_or_b32_e32 v22, s10, v2
	v_or_b32_e32 v17, s7, v3
	s_waitcnt vmcnt(1)
	ds_write_b32 v18, v23
	s_waitcnt vmcnt(0)
	ds_write_b32 v20, v24
	s_sleep 32
	v_or_b32_e32 v18, s10, v0
	v_or_b32_e32 v20, s7, v7
	v_mad_i64_i32 v[18:19], s[10:11], v18, s31, v[10:11]
	v_mad_i64_i32 v[20:21], s[10:11], v20, s31, v[10:11]
	global_load_dword v23, v[18:19], off
	global_load_dword v24, v[20:21], off
	v_mad_u64_u32 v[18:19], s[10:11], v22, s83, v[6:7]
	v_mad_u64_u32 v[20:21], s[10:11], v17, s83, v[6:7]
	s_waitcnt vmcnt(1)
	ds_write_b32 v18, v23
	s_waitcnt vmcnt(0)
	ds_write_b32 v20, v24
	s_sleep 32
	s_cbranch_scc1 .LBB0_841
; #define LAS __attribute__((address_space(3)))
; __device__ __forceinline__ unsigned pkbf(float lo, float hi) { f32x2 v = {lo, hi}; bf16x2v b = __builtin_convertvector(v, bf16x2v); return __builtin_bit_cast(unsigned, b); }
; template <int MODE> __device__ __forceinline__ void transpose_item(const float* W, int K, int N, bf16_t* WT, LAS float* scr, int item, int lane) {
;     ...
;     asm volatile("s_waitcnt lgkmcnt(0)" ::: "memory");
;     const int c = lane & 7;
; #pragma unroll
;     for (int j = 0; j < 4; ++j) {
;         const int n = (lane >> 3) + 8 * j, gn = n0 + n; const LAS float* s = scr + (8 * c) * 33 + n;
;         const int drow = MODE == 0 ? gn : (MODE == 1 ? (gn >= 8608 ? gn + 96 : gn) : (gn < DFF ? 2 * gn : 2 * (gn - DFF) + 1));
;         u32x4 o; o.x = pkbf(s[0 * 33], s[1 * 33]); o.y = pkbf(s[2 * 33], s[3 * 33]); o.z = pkbf(s[4 * 33], s[5 * 33]); o.w = pkbf(s[6 * 33], s[7 * 33]);
;         *(u32x4*)(WT + (size_t)drow * K + k0 + 8 * c) = o;
;     }
;     asm volatile("s_waitcnt lgkmcnt(0)" ::: "memory");
; __device__ __forceinline__ void ph_wconv(CArgs& a, int l, unsigned char* ldsg, int gw, int ngw, int lane, int wv, int mask) {
;     ...
;     if (mask & 8) for (int it = gw; it < I_WI; it += ngw) transpose_item<2>(a.in[31] + (size_t)l * 1024 * 5632, 1024, 5632, (bf16_t*)(ws + WS_WI), scr, it, lane);
	s_waitcnt lgkmcnt(0)
	v_or_b32_e32 v0, s40, v12
	v_cmp_gt_i32_e32 vcc, s30, v0
	v_lshlrev_b32_e32 v0, 1, v0
	ds_read2_b32 v[24:25], v13 offset0:33 offset1:41
	ds_read2_b32 v[26:27], v13 offset1:8
	ds_read2_b32 v[28:29], v13 offset0:66 offset1:74
	ds_read2_b32 v[30:31], v13 offset0:99 offset1:107
	ds_read2_b32 v[32:33], v13 offset0:132 offset1:140
	ds_read2_b32 v[34:35], v13 offset0:165 offset1:173
	ds_read2_b32 v[36:37], v13 offset0:198 offset1:206
	ds_read2_b32 v[38:39], v13 offset0:231 offset1:239
	v_add_u32_e32 v7, 0xffffea01, v0
	v_cndmask_b32_e32 v22, v7, v0, vcc
	s_ashr_i32 s43, s42, 31
	v_ashrrev_i32_e32 v23, 31, v22
	v_or_b32_e32 v0, s40, v14
	v_lshl_add_u64 v[10:11], s[42:43], 1, v[8:9]
	v_lshlrev_b64 v[22:23], 11, v[22:23]
	v_cmp_gt_i32_e32 vcc, s30, v0
	v_lshlrev_b32_e32 v0, 1, v0
	s_waitcnt lgkmcnt(6)
	v_cvt_pk_bf16_f32 v18, v26, v24
	s_waitcnt lgkmcnt(4)
	v_cvt_pk_bf16_f32 v19, v28, v30
	s_waitcnt lgkmcnt(2)
	v_cvt_pk_bf16_f32 v20, v32, v34
	s_waitcnt lgkmcnt(0)
	v_cvt_pk_bf16_f32 v21, v36, v38
	v_lshl_add_u64 v[22:23], v[10:11], 0, v[22:23]
	v_add_u32_e32 v7, 0xffffea01, v0
	global_store_dwordx4 v[22:23], v[18:21], off
	v_cndmask_b32_e32 v22, v7, v0, vcc
	v_ashrrev_i32_e32 v23, 31, v22
	v_lshlrev_b64 v[22:23], 11, v[22:23]
	v_cvt_pk_bf16_f32 v18, v27, v25
	v_cvt_pk_bf16_f32 v19, v29, v31
	v_cvt_pk_bf16_f32 v20, v33, v35
	v_cvt_pk_bf16_f32 v21, v37, v39
	v_lshl_add_u64 v[22:23], v[10:11], 0, v[22:23]
	global_store_dwordx4 v[22:23], v[18:21], off
	v_or_b32_e32 v0, s40, v15
	v_cmp_gt_i32_e32 vcc, s30, v0
	v_lshlrev_b32_e32 v0, 1, v0
	ds_read2_b32 v[24:25], v13 offset0:49 offset1:57
	ds_read2_b32 v[26:27], v13 offset0:16 offset1:24
	ds_read2_b32 v[28:29], v13 offset0:82 offset1:90
	ds_read2_b32 v[30:31], v13 offset0:115 offset1:123
	ds_read2_b32 v[32:33], v13 offset0:148 offset1:156
	ds_read2_b32 v[34:35], v13 offset0:181 offset1:189
	ds_read2_b32 v[36:37], v13 offset0:214 offset1:222
	ds_read2_b32 v[38:39], v13 offset0:247 offset1:255
	v_add_u32_e32 v7, 0xffffea01, v0
	v_cndmask_b32_e32 v22, v7, v0, vcc
	v_ashrrev_i32_e32 v23, 31, v22
	v_or_b32_e32 v0, s40, v16
	v_lshlrev_b64 v[22:23], 11, v[22:23]
	v_cmp_gt_i32_e32 vcc, s30, v0
	v_lshlrev_b32_e32 v0, 1, v0
	s_waitcnt lgkmcnt(6)
	v_cvt_pk_bf16_f32 v18, v26, v24
	s_waitcnt lgkmcnt(4)
	v_cvt_pk_bf16_f32 v19, v28, v30
	s_waitcnt lgkmcnt(2)
	v_cvt_pk_bf16_f32 v20, v32, v34
	s_waitcnt lgkmcnt(0)
	v_cvt_pk_bf16_f32 v21, v36, v38
	v_lshl_add_u64 v[22:23], v[10:11], 0, v[22:23]
	v_add_u32_e32 v7, 0xffffea01, v0
	global_store_dwordx4 v[22:23], v[18:21], off
	v_cndmask_b32_e32 v22, v7, v0, vcc
	v_ashrrev_i32_e32 v23, 31, v22
	v_lshlrev_b64 v[22:23], 11, v[22:23]
	v_cvt_pk_bf16_f32 v18, v27, v25
	v_cvt_pk_bf16_f32 v19, v29, v31
	v_cvt_pk_bf16_f32 v20, v33, v35
	v_cvt_pk_bf16_f32 v21, v37, v39
	v_lshl_add_u64 v[10:11], v[10:11], 0, v[22:23]
	global_store_dwordx4 v[10:11], v[18:21], off
	s_waitcnt lgkmcnt(0)
	s_add_i32 s1, s1, s3
	s_cmpk_gt_i32 s1, 0xaff
	s_cbranch_scc0 .LBB0_840
